# v24 plus producer-list sync after attention and relaxed ffn_in head waits
# speedup vs baseline: 1.0014x; 1.0014x over previous
.LBB0_29:
	s_add_i32 s29, s41, 1
	s_movk_i32 s30, 0xe000
	v_add_co_u32_e32 v60, vcc, s30, v96
	s_bitcmp1_b32 s41, 0
	s_mov_b64 s[30:31], 0x4000
	global_load_dwordx4 v[40:43], v[96:97], off
	global_load_dwordx4 v[32:35], v[98:99], off
	global_load_dwordx4 v[36:39], v[100:101], off
	v_addc_co_u32_e32 v61, vcc, -1, v97, vcc
	v_lshl_add_u64 v[96:97], v[96:97], 0, s[30:31]
	s_cselect_b32 s30, 0xd800, 0
	v_add_u32_e32 v127, s30, v125
	global_load_dwordx4 v[60:63], v[60:61], off
	ds_read_b128 v[66:69], v127
	ds_read_b128 v[70:73], v127 offset:4608
	ds_read_b128 v[110:113], v127 offset:64
	ds_read_b128 v[128:131], v127 offset:4672
	v_mov_b32_e32 v64, v103
	s_waitcnt vmcnt(7) lgkmcnt(3)
	v_mfma_f32_16x16x32_bf16 v[66:69], v[66:69], v[12:15], 0
	ds_read_b128 v[102:105], v127 offset:9216
	ds_read_b128 v[106:109], v127 offset:13824
	v_mov_b32_e32 v126, v65
	s_waitcnt lgkmcnt(4)
	v_mfma_f32_16x16x32_bf16 v[70:73], v[70:73], v[12:15], 0
	s_bitcmp1_b32 s29, 0
	s_cselect_b32 s30, 0xd800, 0
	s_add_i32 s30, s30, 0
	s_waitcnt vmcnt(6) lgkmcnt(3)
	v_mfma_f32_16x16x32_bf16 v[66:69], v[110:113], v[8:11], v[66:69]
	ds_read_b128 v[110:113], v127 offset:9280
	v_lshl_add_u64 v[98:99], v[98:99], 0, s[86:87]
	v_lshl_add_u64 v[100:101], v[100:101], 0, s[86:87]
	s_waitcnt lgkmcnt(3)
	v_mfma_f32_16x16x32_bf16 v[70:73], v[128:131], v[8:11], v[70:73]
	ds_read_b128 v[128:131], v127 offset:13888
	s_mov_b32 s41, s29
	s_cmp_eq_u32 s28, s29
	s_waitcnt lgkmcnt(3)
	v_mfma_f32_16x16x32_bf16 v[102:105], v[102:105], v[12:15], 0
	s_waitcnt lgkmcnt(2)
	v_mfma_f32_16x16x32_bf16 v[106:109], v[106:109], v[12:15], 0
	s_waitcnt lgkmcnt(1)
	v_mfma_f32_16x16x32_bf16 v[102:105], v[110:113], v[8:11], v[102:105]
	ds_read_b128 v[110:113], v127 offset:128
	s_waitcnt lgkmcnt(1)
	v_mfma_f32_16x16x32_bf16 v[106:109], v[128:131], v[8:11], v[106:109]
	ds_read_b128 v[128:131], v127 offset:4736
	s_waitcnt vmcnt(5) lgkmcnt(1)
	v_mfma_f32_16x16x32_bf16 v[66:69], v[110:113], v[4:7], v[66:69]
	ds_read_b128 v[110:113], v127 offset:9344
	s_waitcnt lgkmcnt(1)
	v_mfma_f32_16x16x32_bf16 v[128:131], v[128:131], v[4:7], v[70:73]
	s_nop 2
	ds_read_b128 v[70:73], v127 offset:13952
	s_waitcnt lgkmcnt(1)
	v_mfma_f32_16x16x32_bf16 v[102:105], v[110:113], v[4:7], v[102:105]
	ds_read_b128 v[110:113], v127 offset:192
	ds_read_b128 v[132:135], v127 offset:4800
	ds_read_b128 v[136:139], v127 offset:9408
	ds_read_b128 v[140:143], v127 offset:14016
	ds_read_b128 v[148:151], v127 offset:18432
	s_waitcnt lgkmcnt(5)
	v_mfma_f32_16x16x32_bf16 v[106:109], v[70:73], v[4:7], v[106:109]
	s_waitcnt vmcnt(4) lgkmcnt(4)
	v_mfma_f32_16x16x32_bf16 v[66:69], v[110:113], v[0:3], v[66:69]
	ds_read_b128 v[152:155], v127 offset:18496
	ds_read_b128 v[112:115], v127 offset:23040
	ds_read_b128 v[72:75], v127 offset:23104
	s_waitcnt lgkmcnt(6)
	v_mfma_f32_16x16x32_bf16 v[128:131], v[132:135], v[0:3], v[128:131]
	s_nop 2
	v_max3_f32 v65, v66, v67, v68
	ds_read_b128 v[132:135], v127 offset:27648
	ds_read_b128 v[174:177], v127 offset:32256
	ds_read_b128 v[178:181], v127 offset:36864
	ds_read_b128 v[182:185], v127 offset:41472
	ds_read_b128 v[186:189], v127 offset:46080
	ds_read_b128 v[190:193], v127 offset:50688
	s_waitcnt lgkmcnt(11)
	v_mfma_f32_16x16x32_bf16 v[136:139], v[136:139], v[0:3], v[102:105]
	v_max_f32_e32 v70, v130, v130
	v_max_f32_e32 v71, v129, v129
	v_max3_f32 v65, v65, v69, v128
	s_waitcnt lgkmcnt(10)
	v_mfma_f32_16x16x32_bf16 v[104:107], v[140:143], v[0:3], v[106:109]
	v_max_f32_e32 v70, v71, v70
	s_nop 1
	v_max_f32_e32 v103, v138, v138
	v_max3_f32 v65, v65, v70, v131
	v_max_f32_e32 v108, v137, v137
	v_max_f32_e32 v71, v108, v103
	s_nop 0
	v_max_f32_e32 v109, v106, v106
	v_max_f32_e32 v110, v105, v105
	v_max3_f32 v65, v65, v136, v71
	v_max_f32_e32 v103, v110, v109
	v_max3_f32 v65, v65, v139, v104
	v_max3_f32 v65, v65, v103, v107
	ds_bpermute_b32 v70, v121, v65
	v_mov_b32_e32 v102, v104
	s_waitcnt lgkmcnt(0)
	v_max_f32_e32 v70, v70, v70
	v_max_f32_e32 v65, v65, v70
	ds_bpermute_b32 v70, v122, v65
	s_waitcnt lgkmcnt(0)
	v_max3_f32 v103, v64, v65, v70
	v_sub_f32_e32 v70, v64, v103
	v_pk_mul_f32 v[64:65], v[102:103], s[56:57]
	v_mul_f32_e32 v70, 0x3e0293ee, v70
	v_fmamk_f32 v66, v66, 0x3e0293ee, v65
	v_fmamk_f32 v67, v67, 0x3e0293ee, v65
	v_fmamk_f32 v68, v68, 0x3e0293ee, v65
	v_fmamk_f32 v69, v69, 0x3e0293ee, v65
	v_fmamk_f32 v71, v128, 0x3e0293ee, v65
	v_fmamk_f32 v108, v129, 0x3e0293ee, v65
	v_fmamk_f32 v109, v130, 0x3e0293ee, v65
	v_fmamk_f32 v110, v131, 0x3e0293ee, v65
	v_fmamk_f32 v111, v136, 0x3e0293ee, v65
	v_fmamk_f32 v130, v137, 0x3e0293ee, v65
	v_fmamk_f32 v131, v138, 0x3e0293ee, v65
	v_fmamk_f32 v136, v139, 0x3e0293ee, v65
	v_add_f32_e32 v64, v64, v65
	v_fmamk_f32 v137, v105, 0x3e0293ee, v65
	v_fmamk_f32 v138, v106, 0x3e0293ee, v65
	v_fmac_f32_e32 v65, 0x3e0293ee, v107
	v_exp_f32_e32 v102, v70
	v_exp_f32_e32 v104, v66
	v_exp_f32_e32 v106, v67
	v_exp_f32_e32 v105, v68
	v_exp_f32_e32 v107, v69
	v_exp_f32_e32 v66, v71
	v_exp_f32_e32 v128, v108
	v_exp_f32_e32 v67, v109
	v_exp_f32_e32 v129, v110
	v_cvt_pk_bf16_f32 v68, v104, v106
	v_cvt_pk_bf16_f32 v69, v105, v107
	v_cvt_pk_bf16_f32 v70, v66, v128
	v_cvt_pk_bf16_f32 v71, v67, v129
	v_mul_f32_e32 v26, v102, v26
	v_mul_f32_e32 v27, v102, v27
	v_mul_f32_e32 v24, v102, v24
	v_mul_f32_e32 v25, v102, v25
	v_mul_f32_e32 v22, v102, v22
	v_mul_f32_e32 v23, v102, v23
	v_mul_f32_e32 v20, v102, v20
	v_mul_f32_e32 v21, v102, v21
	v_mfma_f32_16x16x32_bf16 v[24:27], v[112:115], v[68:71], v[24:27]
	v_add_f32_e64 v114, v66, v128
	v_add_f32_e64 v115, v67, v129
	v_exp_f32_e32 v109, v111
	v_pk_add_f32 v[114:115], v[114:115], v[114:115] op_sel_hi:[0,1]
	v_exp_f32_e32 v111, v130
	v_exp_f32_e32 v147, v131
	v_exp_f32_e32 v173, v136
	v_exp_f32_e32 v108, v64
	v_mul_f32_e32 v18, v102, v18
	v_mul_f32_e32 v19, v102, v19
	v_mul_f32_e32 v16, v102, v16
	v_mul_f32_e32 v17, v102, v17
	v_exp_f32_e32 v110, v137
	v_exp_f32_e32 v112, v65
	v_mfma_f32_16x16x32_bf16 v[20:23], v[132:135], v[68:71], v[20:23]
	v_mul_f32_e64 v58, v58, v102
	v_mul_f32_e64 v59, v59, v102
	v_mul_f32_e32 v56, v102, v56
	v_mul_f32_e32 v57, v102, v57
	v_mul_f32_e32 v54, v102, v54
	v_mul_f32_e32 v55, v102, v55
	v_mul_f32_e32 v52, v102, v52
	v_mul_f32_e32 v53, v102, v53
	v_mul_f32_e32 v66, v102, v50
	v_mul_f32_e32 v67, v102, v51
	v_mul_f32_e32 v64, v102, v48
	v_mul_f32_e32 v65, v102, v49
	v_mul_f32_e32 v130, v102, v46
	v_mul_f32_e32 v131, v102, v47
	v_mul_f32_e32 v128, v102, v44
	v_mul_f32_e32 v129, v102, v45
	v_mul_f32_e32 v134, v102, v30
	v_mul_f32_e32 v135, v102, v31
	v_mul_f32_e32 v132, v102, v28
	v_mul_f32_e32 v133, v102, v29
	v_exp_f32_e32 v114, v138
	v_mfma_f32_16x16x32_bf16 v[16:19], v[148:151], v[68:71], v[16:19]
	v_cvt_pk_bf16_f32 v28, v109, v111
	v_cvt_pk_bf16_f32 v29, v147, v173
	v_cvt_pk_bf16_f32 v30, v108, v110
	v_mfma_f32_16x16x32_bf16 v[56:59], v[174:177], v[68:71], v[56:59]
	v_cvt_pk_bf16_f32 v31, v114, v112
	v_add3_u32 v48, s30, v123, v119
	v_add_f32_e32 v109, v109, v111
	v_mfma_f32_16x16x32_bf16 v[50:53], v[178:181], v[68:71], v[52:55]
	v_add_f32_e32 v111, v147, v173
	v_mfma_f32_16x16x32_bf16 v[44:47], v[182:185], v[68:71], v[64:67]
	v_mfma_f32_16x16x32_bf16 v[64:67], v[186:189], v[68:71], v[128:131]
	v_mfma_f32_16x16x32_bf16 v[68:71], v[190:193], v[68:71], v[132:135]
	s_nop 1
	ds_read_b128 v[128:131], v127 offset:27712
	ds_read_b128 v[132:135], v127 offset:32320
	v_mfma_f32_16x16x32_bf16 v[24:27], v[72:75], v[28:31], v[24:27]
	ds_read_b128 v[72:75], v127 offset:36928
	ds_read_b128 v[136:139], v127 offset:41536
	ds_read_b128 v[140:143], v127 offset:46144
	s_waitcnt lgkmcnt(4)
	v_mfma_f32_16x16x32_bf16 v[20:23], v[128:131], v[28:31], v[20:23]
	ds_read_b128 v[128:131], v127 offset:50752
	v_add3_u32 v127, s30, v117, v118
	s_waitcnt lgkmcnt(3)
	v_mfma_f32_16x16x32_bf16 v[52:55], v[72:75], v[28:31], v[50:53]
	v_add_f32_e64 v72, v104, v106
	v_add_f32_e64 v73, v105, v107
	v_add_u32_e32 v74, 0x9000, v48
	v_add_f32_e32 v75, v72, v73
	v_add_f32_e32 v113, 0, v75
	v_mfma_f32_16x16x32_bf16 v[16:19], v[152:155], v[28:31], v[16:19]
	v_add_f32_e64 v72, v108, v110
	v_add_f32_e64 v73, v109, v111
	v_mfma_f32_16x16x32_bf16 v[56:59], v[132:135], v[28:31], v[56:59]
	v_add_u32_e32 v132, 0x4800, v48
	s_waitcnt vmcnt(3)
	ds_write_b128 v127, v[40:43] offset:9216
	s_waitcnt vmcnt(0)
	ds_write_b128 v127, v[60:63]
	ds_write2_b64 v132, v[32:33], v[34:35] offset1:2
	ds_write2_b64 v74, v[36:37], v[38:39] offset1:2
	s_waitcnt lgkmcnt(0)
	v_mfma_f32_16x16x32_bf16 v[48:51], v[136:139], v[28:31], v[44:47]
	s_barrier
	v_mfma_f32_16x16x32_bf16 v[44:47], v[140:143], v[28:31], v[64:67]
	s_nop 2
	v_add_f32_e64 v64, v114, v112
	v_add_f32_e64 v65, v115, v113
	v_mfma_f32_16x16x32_bf16 v[28:31], v[128:131], v[28:31], v[68:71]
	v_add_f32_e64 v64, v72, v64
	v_add_f32_e64 v65, v73, v65
	v_add_f32_e32 v65, v64, v65
	v_fmac_f32_e32 v65, v126, v102
	s_cbranch_scc0 .LBB0_29
	v_add3_u32 v100, s30, v120, v124
	ds_read_b128 v[32:35], v100
	ds_read_b128 v[36:39], v100 offset:64
	ds_read_b128 v[40:43], v100 offset:4608
	ds_read_b128 v[60:63], v100 offset:4672
	ds_read_b128 v[66:69], v100 offset:128
	s_lshl_b32 s84, s40, 1
	s_waitcnt lgkmcnt(4)
	v_mfma_f32_16x16x32_bf16 v[32:35], v[32:35], v[12:15], 0
	s_waitcnt lgkmcnt(3)
	v_mfma_f32_16x16x32_bf16 v[32:35], v[36:39], v[8:11], v[32:35]
	ds_read_b128 v[36:39], v100 offset:192
	s_waitcnt lgkmcnt(1)
	v_mfma_f32_16x16x32_bf16 v[32:35], v[66:69], v[4:7], v[32:35]
	ds_read_b128 v[66:69], v100 offset:9344
	v_mfma_f32_16x16x32_bf16 v[40:43], v[40:43], v[12:15], 0
	s_waitcnt lgkmcnt(1)
	v_mfma_f32_16x16x32_bf16 v[32:35], v[36:39], v[0:3], v[32:35]
	ds_read_b128 v[36:39], v100 offset:4736
	v_mfma_f32_16x16x32_bf16 v[40:43], v[60:63], v[8:11], v[40:43]
	ds_read_b128 v[60:63], v100 offset:4800
	s_nop 4
	v_max3_f32 v64, v32, v33, v34
	s_waitcnt lgkmcnt(1)
	v_mfma_f32_16x16x32_bf16 v[36:39], v[36:39], v[4:7], v[40:43]
	s_nop 2
	ds_read_b128 v[40:43], v100 offset:9216
	s_waitcnt lgkmcnt(1)
	v_mfma_f32_16x16x32_bf16 v[36:39], v[60:63], v[0:3], v[36:39]
	ds_read_b128 v[60:63], v100 offset:9280
	s_waitcnt lgkmcnt(1)
	v_mfma_f32_16x16x32_bf16 v[40:43], v[40:43], v[12:15], 0
	s_nop 4
	v_max3_f32 v64, v64, v35, v36
	s_waitcnt lgkmcnt(0)
	v_mfma_f32_16x16x32_bf16 v[40:43], v[60:63], v[8:11], v[40:43]
	ds_read_b128 v[60:63], v100 offset:9408
	v_mfma_f32_16x16x32_bf16 v[40:43], v[66:69], v[4:7], v[40:43]
	ds_read_b128 v[66:69], v100 offset:13824
	ds_read_b128 v[70:73], v100 offset:13888
	s_waitcnt lgkmcnt(1)
	v_mfma_f32_16x16x32_bf16 v[12:15], v[66:69], v[12:15], 0
	v_max_f32_e32 v66, v38, v38
	v_max_f32_e32 v67, v37, v37
	v_mfma_f32_16x16x32_bf16 v[40:43], v[60:63], v[0:3], v[40:43]
	ds_read_b128 v[60:63], v100 offset:13952
	ds_read_b128 v[96:99], v100 offset:14016
	s_waitcnt lgkmcnt(2)
	v_mfma_f32_16x16x32_bf16 v[8:11], v[70:73], v[8:11], v[12:15]
	s_waitcnt lgkmcnt(1)
	v_mfma_f32_16x16x32_bf16 v[4:7], v[60:63], v[4:7], v[8:11]
	s_nop 0
	v_max_f32_e32 v12, v67, v66
	v_max_f32_e32 v13, v42, v42
	v_max3_f32 v12, v64, v12, v39
	s_waitcnt lgkmcnt(0)
	v_mfma_f32_16x16x32_bf16 v[0:3], v[96:99], v[0:3], v[4:7]
	v_max_f32_e32 v8, v41, v41
	v_max_f32_e32 v8, v8, v13
	v_max3_f32 v8, v12, v40, v8
	s_nop 4
	v_max_f32_e32 v5, v2, v2
	v_max_f32_e32 v6, v1, v1
	v_max3_f32 v4, v8, v43, v0
	v_max_f32_e32 v5, v6, v5
	v_max3_f32 v4, v4, v5, v3
	ds_bpermute_b32 v5, v121, v4
	s_waitcnt lgkmcnt(0)
	v_max_f32_e32 v5, v5, v5
	v_max_f32_e32 v60, v4, v5
	ds_bpermute_b32 v61, v122, v60
	ds_read_b128 v[4:7], v100 offset:18432
	ds_read_b128 v[8:11], v100 offset:18496
	ds_read_b128 v[12:15], v100 offset:23040
	s_waitcnt lgkmcnt(3)
	v_max3_f32 v61, v103, v60, v61
	v_sub_f32_e32 v60, v103, v61
	v_mul_f32_e32 v60, 0x3e0293ee, v60
	v_exp_f32_e32 v64, v60
	v_mov_b32_e32 v60, v3
	v_pk_mul_f32 v[60:61], v[60:61], s[56:57]
	v_pk_mul_f32 v[22:23], v[22:23], v[64:65] op_sel_hi:[1,0]
	v_fmamk_f32 v3, v32, 0x3e0293ee, v61
	v_exp_f32_e32 v66, v3
	v_fmamk_f32 v3, v33, 0x3e0293ee, v61
	v_fmamk_f32 v33, v37, 0x3e0293ee, v61
	v_exp_f32_e32 v68, v3
	v_fmamk_f32 v3, v34, 0x3e0293ee, v61
	v_fmamk_f32 v32, v36, 0x3e0293ee, v61
	v_exp_f32_e32 v36, v33
	v_fmamk_f32 v33, v38, 0x3e0293ee, v61
	v_fmamk_f32 v34, v39, 0x3e0293ee, v61
	v_exp_f32_e32 v32, v32
	v_exp_f32_e32 v33, v33
	v_exp_f32_e32 v37, v34
	v_exp_f32_e32 v67, v3
	v_fmamk_f32 v3, v35, 0x3e0293ee, v61
	v_exp_f32_e32 v69, v3
	v_fmamk_f32 v3, v40, 0x3e0293ee, v61
	v_fmamk_f32 v0, v0, 0x3e0293ee, v61
	v_pk_add_f32 v[34:35], v[32:33], v[36:37]
	v_exp_f32_e32 v73, v3
	v_fmamk_f32 v3, v41, 0x3e0293ee, v61
	v_exp_f32_e32 v72, v0
	v_fmamk_f32 v0, v1, 0x3e0293ee, v61
	v_pk_add_f32 v[70:71], v[34:35], v[34:35] op_sel_hi:[0,1]
	v_exp_f32_e32 v75, v3
	v_fmamk_f32 v3, v42, 0x3e0293ee, v61
	v_exp_f32_e32 v74, v0
	v_fmamk_f32 v0, v2, 0x3e0293ee, v61
	v_exp_f32_e32 v97, v3
	v_fmamk_f32 v3, v43, 0x3e0293ee, v61
	v_exp_f32_e32 v70, v0
	v_add_f32_e32 v0, v60, v61
	v_exp_f32_e32 v98, v3
	v_exp_f32_e32 v96, v0
	v_pk_mul_f32 v[2:3], v[18:19], v[64:65] op_sel_hi:[1,0]
	v_pk_mul_f32 v[0:1], v[16:17], v[64:65] op_sel_hi:[1,0]
	v_cvt_pk_bf16_f32 v16, v66, v68
	v_cvt_pk_bf16_f32 v17, v67, v69
	v_cvt_pk_bf16_f32 v18, v32, v36
	v_cvt_pk_bf16_f32 v19, v33, v37
	v_cvt_pk_bf16_f32 v32, v73, v75
	v_cvt_pk_bf16_f32 v33, v97, v98
	s_waitcnt lgkmcnt(2)
	v_mfma_f32_16x16x32_bf16 v[0:3], v[4:7], v[16:19], v[0:3]
	ds_read_b128 v[4:7], v100 offset:23104
	v_cvt_pk_bf16_f32 v34, v72, v74
	v_cvt_pk_bf16_f32 v35, v70, v96
	v_pk_mul_f32 v[20:21], v[20:21], v[64:65] op_sel_hi:[1,0]
	v_pk_mul_f32 v[54:55], v[54:55], v[64:65] op_sel_hi:[1,0]
	s_waitcnt lgkmcnt(2)
	v_mfma_f32_16x16x32_bf16 v[0:3], v[8:11], v[32:35], v[0:3]
	v_mul_f32_e64 v10, v26, v64
	v_mul_f32_e64 v11, v27, v64
	v_pk_mul_f32 v[8:9], v[24:25], v[64:65] op_sel_hi:[1,0]
	v_pk_mul_f32 v[26:27], v[58:59], v[64:65] op_sel_hi:[1,0]
	v_pk_mul_f32 v[24:25], v[56:57], v[64:65] op_sel_hi:[1,0]
	s_waitcnt lgkmcnt(1)
	v_mfma_f32_16x16x32_bf16 v[8:11], v[12:15], v[16:19], v[8:11]
	ds_read_b128 v[12:15], v100 offset:27648
	v_pk_mul_f32 v[52:53], v[52:53], v[64:65] op_sel_hi:[1,0]
	v_pk_add_f32 v[66:67], v[66:67], v[68:69]
	s_waitcnt lgkmcnt(1)
	v_mfma_f32_16x16x32_bf16 v[4:7], v[4:7], v[32:35], v[8:11]
	v_add_f32_e32 v66, v66, v67
	v_add_f32_e32 v73, v73, v75
	v_add_f32_e32 v75, v97, v98
	ds_read_b128 v[8:11], v100 offset:27712
	s_waitcnt lgkmcnt(1)
	v_mfma_f32_16x16x32_bf16 v[12:15], v[12:15], v[16:19], v[20:23]
	v_add_f32_e32 v97, 0, v66
	v_pk_mul_f32 v[30:31], v[30:31], v[64:65] op_sel_hi:[1,0]
	s_nop 0
	ds_read_b128 v[20:23], v100 offset:32256
	s_waitcnt lgkmcnt(1)
	v_mfma_f32_16x16x32_bf16 v[8:11], v[8:11], v[32:35], v[12:15]
	s_nop 2
	ds_read_b128 v[12:15], v100 offset:32320
	v_pk_mul_f32 v[28:29], v[28:29], v[64:65] op_sel_hi:[1,0]
	s_waitcnt lgkmcnt(1)
	v_mfma_f32_16x16x32_bf16 v[20:23], v[20:23], v[16:19], v[24:27]
	s_nop 2
	ds_read_b128 v[24:27], v100 offset:36864
	ds_read_b128 v[36:39], v100 offset:36928
	s_waitcnt lgkmcnt(1)
	v_mfma_f32_16x16x32_bf16 v[24:27], v[24:27], v[16:19], v[52:55]
	v_mfma_f32_16x16x32_bf16 v[12:15], v[12:15], v[32:35], v[20:23]
	s_nop 2
	ds_read_b128 v[20:23], v100 offset:41472
	ds_read_b128 v[40:43], v100 offset:41536
	ds_read_b128 v[52:55], v100 offset:46080
	ds_read_b128 v[56:59], v100 offset:46144
	ds_read_b128 v[60:63], v100 offset:50688
	s_waitcnt lgkmcnt(5)
	v_mfma_f32_16x16x32_bf16 v[24:27], v[36:39], v[32:35], v[24:27]
	v_mul_f32_e64 v38, v50, v64
	v_mul_f32_e64 v39, v51, v64
	v_pk_mul_f32 v[36:37], v[48:49], v[64:65] op_sel_hi:[1,0]
	s_waitcnt lgkmcnt(4)
	s_nop 0
	v_mfma_f32_16x16x32_bf16 v[20:23], v[20:23], v[16:19], v[36:39]
	s_waitcnt lgkmcnt(3)
	v_mfma_f32_16x16x32_bf16 v[20:23], v[40:43], v[32:35], v[20:23]
	v_add_f32_e64 v40, v72, v74
	v_add_f32_e64 v41, v73, v75
	v_pk_add_f32 v[42:43], v[70:71], v[96:97]
	v_pk_mul_f32 v[36:37], v[44:45], v[64:65] op_sel_hi:[1,0]
	v_pk_add_f32 v[40:41], v[40:41], v[42:43]
	v_pk_mul_f32 v[38:39], v[46:47], v[64:65] op_sel_hi:[1,0]
	v_add_f32_e32 v44, v40, v41
	v_fmac_f32_e32 v44, v65, v64
	ds_bpermute_b32 v45, v121, v44
	s_waitcnt lgkmcnt(3)
	v_mfma_f32_16x16x32_bf16 v[36:39], v[52:55], v[16:19], v[36:39]
	ds_read_b128 v[40:43], v100 offset:50752
	s_waitcnt lgkmcnt(0)
	s_barrier
	v_mfma_f32_16x16x32_bf16 v[16:19], v[60:63], v[16:19], v[28:31]
	s_nop 2
	v_add_f32_e32 v28, v44, v45
	ds_bpermute_b32 v29, v122, v28
	v_mfma_f32_16x16x32_bf16 v[36:39], v[56:59], v[32:35], v[36:39]
	s_waitcnt lgkmcnt(0)
	v_add_f32_e32 v28, v28, v29
	v_div_scale_f32 v29, s[28:29], v28, v28, 1.0
	v_rcp_f32_e32 v30, v29
	v_mfma_f32_16x16x32_bf16 v[16:19], v[40:43], v[32:35], v[16:19]
	v_fma_f32 v31, -v29, v30, 1.0
	v_fmac_f32_e32 v30, v31, v30
	v_div_scale_f32 v31, vcc, 1.0, v28, 1.0
	v_mul_f32_e32 v32, v31, v30
	v_fma_f32 v33, -v29, v32, v31
	v_fmac_f32_e32 v32, v33, v30
	v_fma_f32 v29, -v29, v32, v31
	v_div_fmas_f32 v29, v29, v30, v32
	v_div_fixup_f32 v28, v29, v28, 1.0
	v_lshl_add_u64 v[30:31], s[24:25], 0, v[94:95]
	v_lshl_add_u64 v[30:31], v[30:31], 0, s[84:85]
	v_pk_mul_f32 v[2:3], v[2:3], v[28:29] op_sel_hi:[1,0]
	v_pk_mul_f32 v[0:1], v[0:1], v[28:29] op_sel_hi:[1,0]
	v_lshl_add_u64 v[30:31], v[30:31], 0, v[144:145]
	v_cvt_pk_bf16_f32 v0, v0, v1
	v_cvt_pk_bf16_f32 v1, v2, v3
	global_store_dwordx2 v[30:31], v[0:1], off sc1
	v_pk_mul_f32 v[0:1], v[6:7], v[28:29] op_sel_hi:[1,0]
	v_pk_mul_f32 v[2:3], v[4:5], v[28:29] op_sel_hi:[1,0]
	s_nop 0
	v_cvt_pk_bf16_f32 v2, v2, v3
	v_cvt_pk_bf16_f32 v3, v0, v1
	global_store_dwordx2 v[30:31], v[2:3], off offset:32 sc1
	v_pk_mul_f32 v[0:1], v[10:11], v[28:29] op_sel_hi:[1,0]
	v_pk_mul_f32 v[2:3], v[8:9], v[28:29] op_sel_hi:[1,0]
	s_nop 0
	v_cvt_pk_bf16_f32 v2, v2, v3
	v_cvt_pk_bf16_f32 v3, v0, v1
	global_store_dwordx2 v[30:31], v[2:3], off offset:64 sc1
	v_pk_mul_f32 v[0:1], v[14:15], v[28:29] op_sel_hi:[1,0]
	v_pk_mul_f32 v[2:3], v[12:13], v[28:29] op_sel_hi:[1,0]
	s_nop 0
	v_cvt_pk_bf16_f32 v2, v2, v3
	v_cvt_pk_bf16_f32 v3, v0, v1
	global_store_dwordx2 v[30:31], v[2:3], off offset:96 sc1
	v_pk_mul_f32 v[0:1], v[26:27], v[28:29] op_sel_hi:[1,0]
	v_pk_mul_f32 v[2:3], v[24:25], v[28:29] op_sel_hi:[1,0]
	s_nop 0
	v_cvt_pk_bf16_f32 v2, v2, v3
	v_cvt_pk_bf16_f32 v3, v0, v1
	global_store_dwordx2 v[30:31], v[2:3], off offset:128 sc1
	v_pk_mul_f32 v[0:1], v[22:23], v[28:29] op_sel_hi:[1,0]
	v_pk_mul_f32 v[2:3], v[20:21], v[28:29] op_sel_hi:[1,0]
	s_nop 0
	v_cvt_pk_bf16_f32 v2, v2, v3
	v_cvt_pk_bf16_f32 v3, v0, v1
	global_store_dwordx2 v[30:31], v[2:3], off offset:160 sc1
	v_pk_mul_f32 v[0:1], v[38:39], v[28:29] op_sel_hi:[1,0]
	v_pk_mul_f32 v[2:3], v[36:37], v[28:29] op_sel_hi:[1,0]
	s_nop 0
	v_cvt_pk_bf16_f32 v2, v2, v3
	v_cvt_pk_bf16_f32 v3, v0, v1
	global_store_dwordx2 v[30:31], v[2:3], off offset:192 sc1
	s_load_dword s28, s[80:81], 0x0
	v_pk_mul_f32 v[0:1], v[18:19], v[28:29] op_sel_hi:[1,0]
	v_pk_mul_f32 v[2:3], v[16:17], v[28:29] op_sel_hi:[1,0]
	s_waitcnt lgkmcnt(0)
	s_add_i32 s33, s33, s28
	v_cvt_pk_bf16_f32 v2, v2, v3
	v_cvt_pk_bf16_f32 v3, v0, v1
	s_cmpk_gt_i32 s33, 0x1ff
	global_store_dwordx2 v[30:31], v[2:3], off offset:224 sc1
	s_cbranch_scc0 .LBB0_24

.Lpf_w1:
	s_waitcnt vmcnt(8)
.Lpf_w2:
	s_barrier
	global_load_lds_dwordx4 v[14:15], off
	v_lshl_add_u64 v[14:15], v[2:3], 0, s[86:87]
	s_mov_b32 m0, s46
	v_readfirstlane_b32 s46, v173
	v_add_u32_e32 v174, 0xa000, v147
	global_load_lds_dwordx4 v[14:15], off
	v_lshl_add_u64 v[14:15], v[130:131], 0, s[86:87]
	s_mov_b32 m0, s46
	v_readfirstlane_b32 s46, v174
	v_add_u32_e32 v175, s62, v5
	global_load_lds_dwordx4 v[14:15], off
	v_lshl_add_u64 v[14:15], v[128:129], 0, s[86:87]
	s_mov_b32 m0, s46
	s_mov_b64 s[50:51], 0x40080
	v_readfirstlane_b32 s46, v175
	v_add_u32_e32 v176, 0x2000, v175
	global_load_lds_dwordx4 v[14:15], off
	v_lshl_add_u64 v[0:1], v[0:1], 0, s[50:51]
	s_mov_b32 m0, s46
	v_readfirstlane_b32 s46, v176
	global_load_lds_dwordx4 v[0:1], off
	v_lshl_add_u64 v[0:1], v[2:3], 0, s[50:51]
	s_mov_b32 m0, s46
	v_lshlrev_b32_e32 v2, 13, v9
	global_load_lds_dwordx4 v[0:1], off
	v_lshlrev_b32_e32 v0, 13, v4
	v_and_b32_e32 v0, 0xffffc000, v0
	v_lshl_add_u32 v0, v6, 10, v0
	v_and_b32_e32 v2, 0xffffc000, v2
	v_or_b32_e32 v0, v0, v7
	v_lshl_add_u32 v2, v10, 10, v2
	v_add_u32_sdwa v0, v0, sext(v8) dst_sel:DWORD dst_unused:UNUSED_PAD src0_sel:DWORD src1_sel:WORD_0
	v_mov_b32_e32 v1, v145
	v_or_b32_e32 v2, v2, v11
	s_add_u32 s24, s41, s24
	s_cbranch_vccnz .Lpf_w3
	s_waitcnt vmcnt(6)
	s_branch .Lpf_w4
.Lpf_w3:
	s_waitcnt vmcnt(14)
.Lpf_w4:
	v_lshlrev_b64 v[0:1], 1, v[0:1]
	v_add_u32_sdwa v2, v2, sext(v12) dst_sel:DWORD dst_unused:UNUSED_PAD src0_sel:DWORD src1_sel:WORD_0
	v_mov_b32_e32 v3, v145
	s_addc_u32 s25, 0, s25
	v_lshl_add_u64 v[132:133], s[84:85], 0, v[0:1]
	v_lshlrev_b64 v[2:3], 1, v[2:3]
	v_lshl_add_u64 v[136:137], s[24:25], 0, v[0:1]
	v_mov_b32_e32 v0, 0
	v_lshl_add_u64 v[134:135], s[84:85], 0, v[2:3]
	v_lshl_add_u64 v[138:139], s[24:25], 0, v[2:3]
	s_mov_b32 s24, -2
	v_add_u32_e32 v141, 0, v16
	v_mov_b32_e32 v1, v0
	v_mov_b32_e32 v2, v0
	v_mov_b32_e32 v3, v0
	v_mov_b32_e32 v4, v0
	v_mov_b32_e32 v5, v0
	v_mov_b32_e32 v6, v0
	v_mov_b32_e32 v7, v0
	v_mov_b32_e32 v8, v0
	v_mov_b32_e32 v9, v0
	v_mov_b32_e32 v10, v0
	v_mov_b32_e32 v11, v0
	v_mov_b32_e32 v12, v0
	v_mov_b32_e32 v13, v0
	v_mov_b32_e32 v14, v0
	v_mov_b32_e32 v15, v0
	v_mov_b32_e32 v16, v0
	v_mov_b32_e32 v17, v0
	v_mov_b32_e32 v18, v0
	v_mov_b32_e32 v19, v0
	v_mov_b32_e32 v20, v0
	v_mov_b32_e32 v21, v0
	v_mov_b32_e32 v22, v0
	v_mov_b32_e32 v23, v0
	v_mov_b32_e32 v24, v0
	v_mov_b32_e32 v25, v0
	v_mov_b32_e32 v26, v0
	v_mov_b32_e32 v27, v0
	v_mov_b32_e32 v28, v0
	v_mov_b32_e32 v29, v0
	v_mov_b32_e32 v30, v0
	v_mov_b32_e32 v31, v0
	v_mov_b32_e32 v32, v0
	v_mov_b32_e32 v33, v0
	v_mov_b32_e32 v34, v0
	v_mov_b32_e32 v35, v0
	v_mov_b32_e32 v36, v0
	v_mov_b32_e32 v37, v0
	v_mov_b32_e32 v38, v0
	v_mov_b32_e32 v39, v0
	v_mov_b32_e32 v40, v0
	v_mov_b32_e32 v41, v0
	v_mov_b32_e32 v42, v0
	v_mov_b32_e32 v43, v0
	v_mov_b32_e32 v44, v0
	v_mov_b32_e32 v45, v0
	v_mov_b32_e32 v46, v0
	v_mov_b32_e32 v47, v0
	v_mov_b32_e32 v48, v0
	v_mov_b32_e32 v49, v0
	v_mov_b32_e32 v50, v0
	v_mov_b32_e32 v51, v0
	v_mov_b32_e32 v52, v0
	v_mov_b32_e32 v53, v0
	v_mov_b32_e32 v54, v0
	v_mov_b32_e32 v55, v0
	v_mov_b32_e32 v56, v0
	v_mov_b32_e32 v57, v0
	v_mov_b32_e32 v58, v0
	v_mov_b32_e32 v59, v0
	v_mov_b32_e32 v60, v0
	v_mov_b32_e32 v61, v0
	v_mov_b32_e32 v62, v0
	v_mov_b32_e32 v63, v0
	v_mov_b32_e32 v64, v0
	v_mov_b32_e32 v65, v0
	v_mov_b32_e32 v66, v0
	v_mov_b32_e32 v67, v0
	v_mov_b32_e32 v68, v0
	v_mov_b32_e32 v69, v0
	v_mov_b32_e32 v70, v0
	v_mov_b32_e32 v71, v0
	v_mov_b32_e32 v80, v0
	v_mov_b32_e32 v81, v0
	v_mov_b32_e32 v82, v0
	v_mov_b32_e32 v83, v0
	v_mov_b32_e32 v84, v0
	v_mov_b32_e32 v85, v0
	v_mov_b32_e32 v86, v0
	v_mov_b32_e32 v87, v0
	v_mov_b32_e32 v88, v0
	v_mov_b32_e32 v89, v0
	v_mov_b32_e32 v90, v0
	v_mov_b32_e32 v91, v0
	v_mov_b32_e32 v92, v0
	v_mov_b32_e32 v93, v0
	v_mov_b32_e32 v94, v0
	v_mov_b32_e32 v95, v0
	v_mov_b32_e32 v96, v0
	v_mov_b32_e32 v97, v0
	v_mov_b32_e32 v98, v0
	v_mov_b32_e32 v99, v0
	v_mov_b32_e32 v100, v0
	v_mov_b32_e32 v101, v0
	v_mov_b32_e32 v102, v0
	v_mov_b32_e32 v103, v0
	v_mov_b32_e32 v104, v0
	v_mov_b32_e32 v105, v0
	v_mov_b32_e32 v106, v0
	v_mov_b32_e32 v107, v0
	v_mov_b32_e32 v108, v0
	v_mov_b32_e32 v109, v0
	v_mov_b32_e32 v110, v0
	v_mov_b32_e32 v111, v0
	v_mov_b32_e32 v112, v0
	v_mov_b32_e32 v113, v0
	v_mov_b32_e32 v114, v0
	v_mov_b32_e32 v115, v0
	v_mov_b32_e32 v116, v0
	v_mov_b32_e32 v117, v0
	v_mov_b32_e32 v118, v0
	v_mov_b32_e32 v119, v0
	v_mov_b32_e32 v120, v0
	v_mov_b32_e32 v121, v0
	v_mov_b32_e32 v122, v0
	v_mov_b32_e32 v123, v0
	v_mov_b32_e32 v124, v0
	v_mov_b32_e32 v125, v0
	v_mov_b32_e32 v126, v0
	v_mov_b32_e32 v127, v0
	v_mov_b32_e32 v72, v0
	v_mov_b32_e32 v73, v0
	v_mov_b32_e32 v74, v0
	v_mov_b32_e32 v75, v0
	v_mov_b32_e32 v76, v0
	v_mov_b32_e32 v77, v0
	v_mov_b32_e32 v78, v0
	v_mov_b32_e32 v79, v0
	s_barrier
